# v24 + nt (streaming) hint on phase-0 once-read inputs: x rows and f32 weight tiles
# speedup vs baseline: 1.0160x; 1.0160x over previous
;     __device__ __forceinline__ void row(int r, int col32, int fq, const f32x4& a00, const f32x4& a01, const f32x4& a10, const f32x4& a11) const { half(r, col32, fq, a00, a01); half(r, col32 + HALF, fq, a10, a11); }
;     __device__ __forceinline__ void row(int r, int col32, int fq, const f32x4& a00, const f32x4& a01, const f32x4& a10, const f32x4& a11) const { half(r, col32, fq, a00, a01); half(r, col32 + HALF, fq, a10, a11); }
;     __device__ __forceinline__ void row(int r, int col32, int fq, const f32x4& a00, const f32x4& a01, const f32x4& a10, const f32x4& a11) const { half(r, col32, fq, a00, a01); half(r, col32 + HALF, fq, a10, a11); }
; __device__ __forceinline__ void phase0(const Params& p) {
;     ...
;             const int lane = threadIdx.x & 63, row0 = it * 32 + (threadIdx.x >> 6) * 4;
;             f32x4 v[4][4];
; #pragma unroll
;             for (int r = 0; r < 4; ++r) {
;                 const int row = row0 + r, b = row / TP, t = row - b * TP;
;                 const float* src = t < NMETA ? p.in[1] + (size_t)t * D : p.in[0] + ((size_t)b * SEQ + (t < T ? t - NMETA : 0)) * D;
; #pragma unroll
;                 for (int j = 0; j < 4; ++j) v[r][j] = *(const f32x4*)(src + 4 * lane + 256 * j);
;             }
;             f32x4 g[4];
; #pragma unroll
;             for (int j = 0; j < 4; ++j) g[j] = *(const f32x4*)(p.in[2] + 4 * lane + 256 * j);
.LBB0_22:
	s_cmpk_lt_i32 s11, 0x410
	s_mov_b64 s[4:5], -1
	s_cbranch_scc0 .LBB0_48
	v_mul_hi_i32 v0, v124, s6
	v_lshrrev_b32_e32 v1, 31, v0
	v_ashrrev_i32_e32 v0, 12, v0
	v_add_u32_e32 v150, v0, v1
	v_mad_i32_i24 v0, v150, s7, v124
	v_cmp_lt_i32_e32 vcc, 15, v0
	v_mov_b64_e32 v[2:3], s[58:59]
	s_and_saveexec_b64 s[4:5], vcc
	s_xor_b64 s[4:5], exec, s[4:5]
	v_ashrrev_i32_e32 v151, 31, v150
	v_add_u32_e32 v1, -16, v0
	v_cmp_gt_u32_e32 vcc, s8, v0
	s_nop 1
	v_cndmask_b32_e32 v82, 0, v1, vcc
	v_lshlrev_b64 v[0:1], 25, v[150:151]
	v_lshl_add_u64 v[2:3], s[56:57], 0, v[0:1]
	v_mov_b64_e32 v[0:1], v[82:83]
	s_andn2_saveexec_b64 s[4:5], s[4:5]
	v_ashrrev_i32_e32 v1, 31, v0
	s_or_b64 exec, exec, s[4:5]
	v_lshlrev_b64 v[0:1], 12, v[0:1]
	v_lshl_add_u64 v[0:1], v[2:3], 0, v[0:1]
	v_lshlrev_b32_e32 v82, 2, v80
	v_lshl_add_u64 v[0:1], v[0:1], 0, v[82:83]
	global_load_dwordx4 v[76:79], v[0:1], off nt
	global_load_dwordx4 v[72:75], v[0:1], off offset:1024 nt
	global_load_dwordx4 v[68:71], v[0:1], off offset:2048 nt
	global_load_dwordx4 v[64:67], v[0:1], off offset:3072 nt
	v_add_u32_e32 v144, 1, v124
	v_mul_hi_i32 v0, v144, s6
	v_lshrrev_b32_e32 v1, 31, v0
	v_ashrrev_i32_e32 v0, 12, v0
	v_add_u32_e32 v148, v0, v1
	v_mad_i32_i24 v1, v148, s7, v124
	v_add_u32_e32 v0, 1, v1
	v_cmp_lt_i32_e32 vcc, 15, v0
	v_mov_b64_e32 v[2:3], s[58:59]
	s_and_saveexec_b64 s[4:5], vcc
	s_xor_b64 s[4:5], exec, s[4:5]
	v_ashrrev_i32_e32 v149, 31, v148
	v_add_u32_e32 v1, -15, v1
	v_cmp_gt_u32_e32 vcc, s8, v0
	v_lshlrev_b64 v[2:3], 25, v[148:149]
	v_lshl_add_u64 v[2:3], s[56:57], 0, v[2:3]
	v_cndmask_b32_e32 v0, 0, v1, vcc
	v_mov_b32_e32 v1, v83
	s_andn2_saveexec_b64 s[4:5], s[4:5]
	v_ashrrev_i32_e32 v1, 31, v0
	s_or_b64 exec, exec, s[4:5]
	v_lshlrev_b64 v[0:1], 12, v[0:1]
	v_lshl_add_u64 v[0:1], v[2:3], 0, v[0:1]
	v_lshl_add_u64 v[0:1], v[0:1], 0, v[82:83]
	global_load_dwordx4 v[60:63], v[0:1], off nt
	global_load_dwordx4 v[56:59], v[0:1], off offset:1024 nt
	global_load_dwordx4 v[52:55], v[0:1], off offset:2048 nt
	global_load_dwordx4 v[48:51], v[0:1], off offset:3072 nt
	v_add_u32_e32 v140, 2, v124
	v_mul_hi_i32 v0, v140, s6
	v_lshrrev_b32_e32 v1, 31, v0
	v_ashrrev_i32_e32 v0, 12, v0
	v_add_u32_e32 v146, v0, v1
	v_mad_i32_i24 v1, v146, s7, v124
	v_add_u32_e32 v0, 2, v1
	v_cmp_lt_i32_e32 vcc, 15, v0
	v_mov_b64_e32 v[2:3], s[58:59]
	s_and_saveexec_b64 s[4:5], vcc
	s_xor_b64 s[4:5], exec, s[4:5]
	v_ashrrev_i32_e32 v147, 31, v146
	v_add_u32_e32 v1, -14, v1
	v_cmp_gt_u32_e32 vcc, s8, v0
	v_lshlrev_b64 v[2:3], 25, v[146:147]
	v_lshl_add_u64 v[2:3], s[56:57], 0, v[2:3]
	v_cndmask_b32_e32 v0, 0, v1, vcc
	v_mov_b32_e32 v1, v83
	s_andn2_saveexec_b64 s[4:5], s[4:5]
	v_ashrrev_i32_e32 v1, 31, v0
	s_or_b64 exec, exec, s[4:5]
	v_lshlrev_b64 v[0:1], 12, v[0:1]
	v_lshl_add_u64 v[0:1], v[2:3], 0, v[0:1]
	v_lshl_add_u64 v[0:1], v[0:1], 0, v[82:83]
	global_load_dwordx4 v[44:47], v[0:1], off nt
	global_load_dwordx4 v[40:43], v[0:1], off offset:1024 nt
	global_load_dwordx4 v[36:39], v[0:1], off offset:2048 nt
	global_load_dwordx4 v[32:35], v[0:1], off offset:3072 nt
	v_add_u32_e32 v138, 3, v124
	v_mul_hi_i32 v0, v138, s6
	v_lshrrev_b32_e32 v1, 31, v0
	v_ashrrev_i32_e32 v0, 12, v0
	v_add_u32_e32 v142, v0, v1
	v_mad_i32_i24 v1, v142, s7, v124
	v_add_u32_e32 v0, 3, v1
	v_cmp_lt_i32_e32 vcc, 15, v0
	v_mov_b64_e32 v[2:3], s[58:59]
	s_and_saveexec_b64 s[4:5], vcc
	s_xor_b64 s[4:5], exec, s[4:5]
	v_ashrrev_i32_e32 v143, 31, v142
	v_add_u32_e32 v1, -13, v1
	v_cmp_gt_u32_e32 vcc, s8, v0
	v_lshlrev_b64 v[2:3], 25, v[142:143]
	v_lshl_add_u64 v[2:3], s[56:57], 0, v[2:3]
	v_cndmask_b32_e32 v0, 0, v1, vcc
	v_mov_b32_e32 v1, v83
	s_andn2_saveexec_b64 s[4:5], s[4:5]
	v_ashrrev_i32_e32 v1, 31, v0
	s_or_b64 exec, exec, s[4:5]
	v_lshlrev_b64 v[0:1], 12, v[0:1]
	v_lshl_add_u64 v[0:1], v[2:3], 0, v[0:1]
	v_lshl_add_u64 v[0:1], v[0:1], 0, v[82:83]
	global_load_dwordx4 v[24:27], v[0:1], off nt
	global_load_dwordx4 v[16:19], v[0:1], off offset:1024 nt
	global_load_dwordx4 v[8:11], v[0:1], off offset:2048 nt
	s_nop 0
	global_load_dwordx4 v[0:3], v[0:1], off offset:3072 nt
	s_nop 0
	global_load_dwordx4 v[28:31], v[136:137], off
	global_load_dwordx4 v[20:23], v[136:137], off offset:1024
	global_load_dwordx4 v[12:15], v[136:137], off offset:2048
	global_load_dwordx4 v[4:7], v[136:137], off offset:3072
	v_mul_i32_i24_e32 v82, 0x2080, v150
	v_sub_u32_e32 v82, v124, v82
	v_cmp_gt_i32_e32 vcc, s8, v82
	v_mov_b32_e32 v82, 0
	v_mbcnt_hi_u32_b32 v139, -1, v171
	v_mov_b32_e32 v150, 0
	s_and_saveexec_b64 s[4:5], vcc
	s_cbranch_execz .LBB0_41
; __device__ __forceinline__ void phase0(const Params& p) {
;     ...
;                 float ss = 0.f;
; #pragma unroll
;                 for (int j = 0; j < 4; ++j) ss += (v[r][j][0] * v[r][j][0] + v[r][j][1] * v[r][j][1]) + (v[r][j][2] * v[r][j][2] + v[r][j][3] * v[r][j][3]);
;                 const float rs = t < T ? rsqrtf(wave_sum(ss) * (1.0f / D) + RMS_EPS) : 0.f;
	s_waitcnt vmcnt(19)
	v_pk_mul_f32 v[150:151], v[78:79], v[78:79]
	v_pk_mul_f32 v[166:167], v[76:77], v[76:77]
	v_mov_b32_e32 v175, v151
	v_mov_b32_e32 v174, v166
	v_pk_mov_b32 v[150:151], v[166:167], v[150:151] op_sel:[1,0]
	s_waitcnt vmcnt(18)
	v_pk_mul_f32 v[166:167], v[74:75], v[74:75]
	v_pk_add_f32 v[150:151], v[150:151], v[174:175]
	v_pk_mul_f32 v[174:175], v[72:73], v[72:73]
	v_mov_b32_e32 v177, v167
	v_mov_b32_e32 v176, v174
	v_pk_mov_b32 v[166:167], v[174:175], v[166:167] op_sel:[1,0]
	s_waitcnt vmcnt(16)
	v_mul_f32_e32 v125, v64, v64
	v_pk_add_f32 v[166:167], v[166:167], v[176:177]
	v_mul_f32_e32 v141, v65, v65
	v_pk_add_f32 v[150:151], v[150:151], v[150:151] op_sel:[0,1] op_sel_hi:[1,0]
	v_pk_add_f32 v[166:167], v[166:167], v[166:167] op_sel:[0,1] op_sel_hi:[1,0]
	v_mov_b32_e32 v151, v125
	v_mov_b32_e32 v167, v141
	v_mul_f32_e32 v164, v69, v69
	v_pk_add_f32 v[150:151], v[150:151], v[166:167]
	v_pk_fma_f32 v[166:167], v[68:69], v[68:69], v[164:165] op_sel_hi:[1,1,0]
	v_mul_f32_e32 v164, v71, v71
	v_mul_f32_e32 v143, v66, v66
	v_mul_f32_e32 v145, v67, v67
	v_pk_fma_f32 v[174:175], v[70:71], v[70:71], v[164:165] op_sel_hi:[1,1,0]
	v_and_b32_e32 v141, 64, v139
	v_mov_b32_e32 v167, v143
	v_mov_b32_e32 v175, v145
	v_add_u32_e32 v141, 64, v141
	v_xor_b32_e32 v143, 1, v139
	v_pk_add_f32 v[166:167], v[166:167], v[174:175]
	v_cmp_lt_i32_e32 vcc, v143, v141
	v_pk_add_f32 v[150:151], v[150:151], v[166:167]
	s_nop 0
	v_cndmask_b32_e32 v143, v139, v143, vcc
	v_add_f32_e32 v125, v150, v151
	v_lshlrev_b32_e32 v143, 2, v143
	ds_bpermute_b32 v143, v143, v125
	s_waitcnt lgkmcnt(0)
	v_add_f32_e32 v125, v125, v143
	v_xor_b32_e32 v143, 2, v139
	v_cmp_lt_i32_e32 vcc, v143, v141
	s_nop 1
	v_cndmask_b32_e32 v143, v139, v143, vcc
	v_lshlrev_b32_e32 v143, 2, v143
	ds_bpermute_b32 v143, v143, v125
	s_waitcnt lgkmcnt(0)
	v_add_f32_e32 v125, v125, v143
	v_xor_b32_e32 v143, 4, v139
	v_cmp_lt_i32_e32 vcc, v143, v141
	s_nop 1
	v_cndmask_b32_e32 v143, v139, v143, vcc
	v_lshlrev_b32_e32 v143, 2, v143
	ds_bpermute_b32 v143, v143, v125
	s_waitcnt lgkmcnt(0)
	v_add_f32_e32 v125, v125, v143
	v_xor_b32_e32 v143, 8, v139
	v_cmp_lt_i32_e32 vcc, v143, v141
	s_nop 1
	v_cndmask_b32_e32 v143, v139, v143, vcc
	v_lshlrev_b32_e32 v143, 2, v143
	ds_bpermute_b32 v143, v143, v125
	s_waitcnt lgkmcnt(0)
	v_add_f32_e32 v125, v125, v143
	v_xor_b32_e32 v143, 16, v139
	v_cmp_lt_i32_e32 vcc, v143, v141
	s_nop 1
	v_cndmask_b32_e32 v143, v139, v143, vcc
	v_lshlrev_b32_e32 v143, 2, v143
	ds_bpermute_b32 v143, v143, v125
	s_waitcnt lgkmcnt(0)
	v_add_f32_e32 v125, v125, v143
	v_xor_b32_e32 v143, 32, v139
	v_cmp_lt_i32_e32 vcc, v143, v141
	s_nop 1
	v_cndmask_b32_e32 v141, v139, v143, vcc
	v_lshlrev_b32_e32 v141, 2, v141
	ds_bpermute_b32 v141, v141, v125
	s_waitcnt lgkmcnt(0)
	v_add_f32_e32 v125, v125, v141
	v_fmamk_f32 v125, v125, 0x3a800000, v162
	v_mul_f32_e32 v141, 0x4b800000, v125
	v_cmp_gt_f32_e32 vcc, s9, v125
	s_nop 1
	v_cndmask_b32_e32 v125, v125, v141, vcc
	v_rsq_f32_e32 v125, v125
	s_nop 0
	v_mul_f32_e32 v141, 0x45800000, v125
	v_cndmask_b32_e32 v150, v125, v141, vcc

; __device__ __forceinline__ unsigned pk_bf16(float lo, float hi) { const f32x2 v = {lo, hi}; return __builtin_bit_cast(unsigned, __builtin_convertvector(v, b16x2)); }
; __device__ __forceinline__ void transpose_tile(const float* __restrict__ src, int K, int N, bf16_t* __restrict__ dst, int ldd, int koff, int mode, int tile) {
;     float* scr = (float*)smem;
;     const int ntn = N / 128, kb = tile / ntn, nb = tile % ntn, k0 = kb * 64, n0 = nb * 128, tid = threadIdx.x;
;     f32x4 v[4];
; #pragma unroll
;     for (int i = 0; i < 4; ++i) { const int idx = tid + 512 * i, kk = idx >> 5, n4 = idx & 31; v[i] = *(const f32x4*)(src + (size_t)(k0 + kk) * N + n0 + n4 * 4); }
; #pragma unroll
;     for (int i = 0; i < 4; ++i) { const int idx = tid + 512 * i, kk = idx >> 5, n4 = idx & 31;
; #pragma unroll
;         for (int c = 0; c < 4; ++c) scr[kk * 129 + n4 * 4 + c] = v[i][c]; }
;     __syncthreads();
; #pragma unroll
;     for (int i = 0; i < 2; ++i) {
;         const int o = tid + 512 * i, n = o >> 3, kc = (o & 7) * 8;
;         u32x4 w;
;         w.x = pk_bf16(scr[(kc + 0) * 129 + n], scr[(kc + 1) * 129 + n]); w.y = pk_bf16(scr[(kc + 2) * 129 + n], scr[(kc + 3) * 129 + n]);
;         w.z = pk_bf16(scr[(kc + 4) * 129 + n], scr[(kc + 5) * 129 + n]); w.w = pk_bf16(scr[(kc + 6) * 129 + n], scr[(kc + 7) * 129 + n]);
;         const int f = n0 + n;
;         const int drow = mode == 0 ? f : ((f >> 7) * 256 + (mode == 2 ? 128 : 0) + (f & 127));
;         *(u32x4*)(dst + (size_t)drow * ldd + koff + k0 + kc) = w;
;     }
;     __syncthreads();
; }
; __device__ __forceinline__ void phase0(const Params& p) {
;     ...
;             if (r < J7) { transpose_tile(p.in[6], 64, 512, (bf16_t*)(ws + WS_WL), 256, 0, 0, r); continue; } r -= J7;
;             if (r < J7) { transpose_tile(p.in[8], 64, 512, (bf16_t*)(ws + WS_WL), 256, 64, 0, r); continue; } r -= J7;
;             transpose_tile(p.in[10], 128, 512, (bf16_t*)(ws + WS_WL), 256, 128, 0, r);
.LBB0_48:
	s_and_b64 vcc, exec, s[4:5]
	s_cbranch_vccz .LBB0_21
	s_cmpk_gt_u32 s11, 0x6af
	s_mov_b64 s[4:5], -1
	s_cbranch_scc0 .LBB0_83
	s_cmpk_gt_u32 s11, 0x6ef
	s_cbranch_scc0 .LBB0_80
	s_cmpk_gt_u32 s11, 0x72f
	s_cbranch_scc0 .LBB0_77
	s_cmpk_gt_u32 s11, 0x7af
	s_cbranch_scc0 .LBB0_74
	s_cmpk_gt_u32 s11, 0x90f
	s_cbranch_scc0 .LBB0_71
	s_cmpk_gt_u32 s11, 0xa6f
	s_cbranch_scc0 .LBB0_68
	s_cmpk_gt_u32 s11, 0xbcf
	s_cbranch_scc0 .LBB0_65
	s_cmpk_gt_u32 s11, 0xbd3
	s_cbranch_scc0 .LBB0_62
	s_cmpk_gt_u32 s11, 0xbd7
	s_cbranch_scc0 .LBB0_59
	s_add_i32 s0, s11, 0xf428
	s_and_b32 s4, s0, 0xffff
	s_add_i32 s5, s11, 0xf424
	s_cmp_lt_u32 s4, 4
	s_cselect_b32 s0, s0, s5
	s_cmp_gt_u32 s4, 3
	s_cselect_b32 s4, 64, 0
	s_lshl_b32 s0, s0, 7
	s_and_b32 s5, s0, 0xff80
	s_lshl_b32 s0, s5, 2
	v_or_b32_e32 v0, s4, v165
	v_lshl_add_u64 v[12:13], v[104:105], 0, s[0:1]
	v_lshlrev_b32_e32 v82, 11, v0
	v_or_b32_e32 v0, s4, v81
	v_lshl_add_u64 v[8:9], v[12:13], 0, v[82:83]
	v_lshlrev_b32_e32 v82, 11, v0
	v_lshl_add_u64 v[10:11], v[12:13], 0, v[82:83]
	global_load_dwordx4 v[0:3], v[8:9], off nt
	global_load_dwordx4 v[4:7], v[10:11], off nt
	v_or_b32_e32 v8, s4, v158
	v_lshlrev_b32_e32 v82, 11, v8
	v_lshl_add_u64 v[8:9], v[12:13], 0, v[82:83]
	global_load_dwordx4 v[8:11], v[8:9], off nt
	v_add_lshl_u32 v82, v127, s4, 11
	v_lshl_add_u64 v[12:13], v[12:13], 0, v[82:83]
	global_load_dwordx4 v[12:15], v[12:13], off nt
	v_add_u32_e32 v20, v129, v159
	v_add_u32_e32 v21, v129, v160
	v_add_u32_e32 v22, v129, v161
	v_add_u32_e32 v23, 0x400, v131
	v_add_u32_e32 v24, 0x800, v131
	v_add_u32_e32 v25, 0xc00, v131
	v_add_u32_e32 v26, 0x400, v152
	v_add_u32_e32 v27, 0x800, v152
	v_add_u32_e32 v28, 0xc00, v152
	v_add_u32_e32 v29, 0x4080, v20
	v_add_u32_e32 v30, 0x4088, v20
	v_or_b32_e32 v18, s5, v153
	s_lshl_b32 s0, s4, 1
	v_lshl_add_u64 v[16:17], v[86:87], 0, s[0:1]
	v_lshlrev_b32_e32 v82, 9, v18
	v_lshl_add_u64 v[18:19], v[16:17], 0, v[82:83]
	v_add_lshl_u32 v82, v135, s5, 9
	v_lshl_add_u64 v[16:17], v[16:17], 0, v[82:83]
	s_mov_b64 s[4:5], 0
	s_waitcnt vmcnt(3)
	ds_write2_b32 v20, v0, v1 offset1:1
	ds_write2_b32 v20, v2, v3 offset0:2 offset1:3
	s_waitcnt vmcnt(2)
	ds_write2_b32 v21, v4, v5 offset1:1
	ds_write2_b32 v21, v6, v7 offset0:2 offset1:3
	s_waitcnt vmcnt(1)
	ds_write2_b32 v29, v8, v9 offset1:1
	ds_write2_b32 v30, v10, v11 offset1:1
	s_waitcnt vmcnt(0)
	ds_write2_b32 v22, v12, v13 offset1:1
	ds_write2_b32 v22, v14, v15 offset0:2 offset1:3
	s_waitcnt lgkmcnt(0)
	s_barrier
	ds_read2_b32 v[0:1], v131 offset1:129
	ds_read2_b32 v[2:3], v23 offset0:2 offset1:131
	ds_read2_b32 v[4:5], v24 offset0:4 offset1:133
	ds_read2_b32 v[6:7], v25 offset0:6 offset1:135
	ds_read2_b32 v[8:9], v152 offset1:129
	ds_read2_b32 v[10:11], v26 offset0:2 offset1:131
	ds_read2_b32 v[12:13], v27 offset0:4 offset1:133
	ds_read2_b32 v[14:15], v28 offset0:6 offset1:135
	s_waitcnt lgkmcnt(7)
	v_cvt_pk_bf16_f32 v0, v0, v1
	s_waitcnt lgkmcnt(6)
	v_cvt_pk_bf16_f32 v1, v2, v3
	s_waitcnt lgkmcnt(5)
	v_cvt_pk_bf16_f32 v2, v4, v5
	s_waitcnt lgkmcnt(4)
	v_cvt_pk_bf16_f32 v3, v6, v7
	s_waitcnt lgkmcnt(3)
	v_cvt_pk_bf16_f32 v4, v8, v9
	s_waitcnt lgkmcnt(2)
	v_cvt_pk_bf16_f32 v5, v10, v11
	s_waitcnt lgkmcnt(1)
	v_cvt_pk_bf16_f32 v6, v12, v13
	s_waitcnt lgkmcnt(0)
	v_cvt_pk_bf16_f32 v7, v14, v15
	global_store_dwordx4 v[18:19], v[0:3], off
	global_store_dwordx4 v[16:17], v[4:7], off
	s_barrier
.LBB0_59:
	s_andn2_b64 vcc, exec, s[4:5]
	s_cbranch_vccnz .LBB0_61
	s_lshl_b32 s0, s11, 7
	s_addk_i32 s0, 0x1600
	s_and_b32 s4, s0, 0xff80
	s_lshl_b32 s0, s4, 2
	v_lshl_add_u64 v[12:13], v[106:107], 0, s[0:1]
	v_lshlrev_b32_e32 v82, 2, v126
	v_lshl_add_u64 v[8:9], v[12:13], 0, v[82:83]
	v_lshlrev_b32_e32 v82, 2, v128
	v_lshl_add_u64 v[10:11], v[12:13], 0, v[82:83]
	global_load_dwordx4 v[0:3], v[8:9], off nt
	global_load_dwordx4 v[4:7], v[10:11], off nt
	v_lshlrev_b32_e32 v82, 2, v130
	v_lshl_add_u64 v[8:9], v[12:13], 0, v[82:83]
	global_load_dwordx4 v[8:11], v[8:9], off nt
	v_lshlrev_b32_e32 v82, 2, v134
	v_lshl_add_u64 v[12:13], v[12:13], 0, v[82:83]
	global_load_dwordx4 v[12:15], v[12:13], off nt
	v_add_u32_e32 v20, v129, v159
	v_add_u32_e32 v21, v129, v160
	v_add_u32_e32 v22, v129, v161
	v_add_u32_e32 v23, 0x400, v131
	v_add_u32_e32 v24, 0x800, v131
	v_add_u32_e32 v25, 0xc00, v131
	v_add_u32_e32 v26, 0x400, v152
	v_add_u32_e32 v27, 0x800, v152
	v_add_u32_e32 v28, 0xc00, v152
	v_add_u32_e32 v29, 0x4080, v20
	v_add_u32_e32 v30, 0x4088, v20
	v_or_b32_e32 v16, s4, v153
	v_lshlrev_b32_e32 v82, 9, v16
	v_lshl_add_u64 v[16:17], v[88:89], 0, v[82:83]
	v_add_lshl_u32 v82, v135, s4, 9
	v_lshl_add_u64 v[18:19], v[88:89], 0, v[82:83]
	s_waitcnt vmcnt(3)
	ds_write2_b32 v20, v0, v1 offset1:1
	ds_write2_b32 v20, v2, v3 offset0:2 offset1:3
	s_waitcnt vmcnt(2)
	ds_write2_b32 v21, v4, v5 offset1:1
	ds_write2_b32 v21, v6, v7 offset0:2 offset1:3
	s_waitcnt vmcnt(1)
	ds_write2_b32 v29, v8, v9 offset1:1
	ds_write2_b32 v30, v10, v11 offset1:1
	s_waitcnt vmcnt(0)
	ds_write2_b32 v22, v12, v13 offset1:1
	ds_write2_b32 v22, v14, v15 offset0:2 offset1:3
	s_waitcnt lgkmcnt(0)
	s_barrier
	ds_read2_b32 v[0:1], v131 offset1:129
	ds_read2_b32 v[2:3], v23 offset0:2 offset1:131
	ds_read2_b32 v[4:5], v24 offset0:4 offset1:133
	ds_read2_b32 v[6:7], v25 offset0:6 offset1:135
	ds_read2_b32 v[8:9], v152 offset1:129
	ds_read2_b32 v[10:11], v26 offset0:2 offset1:131
	ds_read2_b32 v[12:13], v27 offset0:4 offset1:133
	ds_read2_b32 v[14:15], v28 offset0:6 offset1:135
	s_waitcnt lgkmcnt(7)
	v_cvt_pk_bf16_f32 v0, v0, v1
	s_waitcnt lgkmcnt(6)
	v_cvt_pk_bf16_f32 v1, v2, v3
	s_waitcnt lgkmcnt(5)
	v_cvt_pk_bf16_f32 v2, v4, v5
	s_waitcnt lgkmcnt(4)
	v_cvt_pk_bf16_f32 v3, v6, v7
	s_waitcnt lgkmcnt(3)
	v_cvt_pk_bf16_f32 v4, v8, v9
	s_waitcnt lgkmcnt(2)
	v_cvt_pk_bf16_f32 v5, v10, v11
	s_waitcnt lgkmcnt(1)
	v_cvt_pk_bf16_f32 v6, v12, v13
	s_waitcnt lgkmcnt(0)
	v_cvt_pk_bf16_f32 v7, v14, v15
	global_store_dwordx4 v[16:17], v[0:3], off
	global_store_dwordx4 v[18:19], v[4:7], off
	s_barrier

; __device__ __forceinline__ unsigned pk_bf16(float lo, float hi) { const f32x2 v = {lo, hi}; return __builtin_bit_cast(unsigned, __builtin_convertvector(v, b16x2)); }
; __device__ __forceinline__ void transpose_tile(const float* __restrict__ src, int K, int N, bf16_t* __restrict__ dst, int ldd, int koff, int mode, int tile) {
;     float* scr = (float*)smem;
;     const int ntn = N / 128, kb = tile / ntn, nb = tile % ntn, k0 = kb * 64, n0 = nb * 128, tid = threadIdx.x;
;     f32x4 v[4];
; #pragma unroll
;     for (int i = 0; i < 4; ++i) { const int idx = tid + 512 * i, kk = idx >> 5, n4 = idx & 31; v[i] = *(const f32x4*)(src + (size_t)(k0 + kk) * N + n0 + n4 * 4); }
; #pragma unroll
;     for (int i = 0; i < 4; ++i) { const int idx = tid + 512 * i, kk = idx >> 5, n4 = idx & 31;
; #pragma unroll
;         for (int c = 0; c < 4; ++c) scr[kk * 129 + n4 * 4 + c] = v[i][c]; }
;     __syncthreads();
; #pragma unroll
;     for (int i = 0; i < 2; ++i) {
;         const int o = tid + 512 * i, n = o >> 3, kc = (o & 7) * 8;
;         u32x4 w;
;         w.x = pk_bf16(scr[(kc + 0) * 129 + n], scr[(kc + 1) * 129 + n]); w.y = pk_bf16(scr[(kc + 2) * 129 + n], scr[(kc + 3) * 129 + n]);
;         w.z = pk_bf16(scr[(kc + 4) * 129 + n], scr[(kc + 5) * 129 + n]); w.w = pk_bf16(scr[(kc + 6) * 129 + n], scr[(kc + 7) * 129 + n]);
;         const int f = n0 + n;
;         const int drow = mode == 0 ? f : ((f >> 7) * 256 + (mode == 2 ? 128 : 0) + (f & 127));
;         *(u32x4*)(dst + (size_t)drow * ldd + koff + k0 + kc) = w;
;     }
;     __syncthreads();
; }
; __device__ __forceinline__ void phase0(const Params& p) {
;     ...
;             if (r < J7) { transpose_tile(p.in[6], 64, 512, (bf16_t*)(ws + WS_WL), 256, 0, 0, r); continue; } r -= J7;
.LBB0_62:
	s_andn2_b64 vcc, exec, s[4:5]
	s_cbranch_vccnz .LBB0_64
	s_lshl_b32 s0, s11, 7
	s_addk_i32 s0, 0x1800
	s_and_b32 s4, s0, 0xff80
	s_lshl_b32 s0, s4, 2
	v_lshl_add_u64 v[12:13], v[108:109], 0, s[0:1]
	v_lshlrev_b32_e32 v82, 2, v126
	v_lshl_add_u64 v[8:9], v[12:13], 0, v[82:83]
	v_lshlrev_b32_e32 v82, 2, v128
	v_lshl_add_u64 v[10:11], v[12:13], 0, v[82:83]
	global_load_dwordx4 v[0:3], v[8:9], off nt
	global_load_dwordx4 v[4:7], v[10:11], off nt
	v_lshlrev_b32_e32 v82, 2, v130
	v_lshl_add_u64 v[8:9], v[12:13], 0, v[82:83]
	global_load_dwordx4 v[8:11], v[8:9], off nt
	v_lshlrev_b32_e32 v82, 2, v134
	v_lshl_add_u64 v[12:13], v[12:13], 0, v[82:83]
	global_load_dwordx4 v[12:15], v[12:13], off nt
	v_add_u32_e32 v20, v129, v159
	v_add_u32_e32 v21, v129, v160
	v_add_u32_e32 v22, v129, v161
	v_add_u32_e32 v23, 0x400, v131
	v_add_u32_e32 v24, 0x800, v131
	v_add_u32_e32 v25, 0xc00, v131
	v_add_u32_e32 v26, 0x400, v152
	v_add_u32_e32 v27, 0x800, v152
	v_add_u32_e32 v28, 0xc00, v152
	v_add_u32_e32 v29, 0x4080, v20
	v_add_u32_e32 v30, 0x4088, v20
	v_or_b32_e32 v16, s4, v153
	v_lshlrev_b32_e32 v82, 9, v16
	v_lshl_add_u64 v[16:17], v[90:91], 0, v[82:83]
	v_add_lshl_u32 v82, v135, s4, 9
	v_lshl_add_u64 v[18:19], v[90:91], 0, v[82:83]
	s_waitcnt vmcnt(3)
	ds_write2_b32 v20, v0, v1 offset1:1
	ds_write2_b32 v20, v2, v3 offset0:2 offset1:3
	s_waitcnt vmcnt(2)
	ds_write2_b32 v21, v4, v5 offset1:1
	ds_write2_b32 v21, v6, v7 offset0:2 offset1:3
	s_waitcnt vmcnt(1)
	ds_write2_b32 v29, v8, v9 offset1:1
	ds_write2_b32 v30, v10, v11 offset1:1
	s_waitcnt vmcnt(0)
	ds_write2_b32 v22, v12, v13 offset1:1
	ds_write2_b32 v22, v14, v15 offset0:2 offset1:3
	s_waitcnt lgkmcnt(0)
	s_barrier
	ds_read2_b32 v[0:1], v131 offset1:129
	ds_read2_b32 v[2:3], v23 offset0:2 offset1:131
	ds_read2_b32 v[4:5], v24 offset0:4 offset1:133
	ds_read2_b32 v[6:7], v25 offset0:6 offset1:135
	ds_read2_b32 v[8:9], v152 offset1:129
	ds_read2_b32 v[10:11], v26 offset0:2 offset1:131
	ds_read2_b32 v[12:13], v27 offset0:4 offset1:133
	ds_read2_b32 v[14:15], v28 offset0:6 offset1:135
	s_waitcnt lgkmcnt(7)
	v_cvt_pk_bf16_f32 v0, v0, v1
	s_waitcnt lgkmcnt(6)
	v_cvt_pk_bf16_f32 v1, v2, v3
	s_waitcnt lgkmcnt(5)
	v_cvt_pk_bf16_f32 v2, v4, v5
	s_waitcnt lgkmcnt(4)
	v_cvt_pk_bf16_f32 v3, v6, v7
	s_waitcnt lgkmcnt(3)
	v_cvt_pk_bf16_f32 v4, v8, v9
	s_waitcnt lgkmcnt(2)
	v_cvt_pk_bf16_f32 v5, v10, v11
	s_waitcnt lgkmcnt(1)
	v_cvt_pk_bf16_f32 v6, v12, v13
	s_waitcnt lgkmcnt(0)
	v_cvt_pk_bf16_f32 v7, v14, v15
	global_store_dwordx4 v[16:17], v[0:3], off
	global_store_dwordx4 v[18:19], v[4:7], off
	s_barrier

; __device__ __forceinline__ unsigned pk_bf16(float lo, float hi) { const f32x2 v = {lo, hi}; return __builtin_bit_cast(unsigned, __builtin_convertvector(v, b16x2)); }
; __device__ __forceinline__ void transpose_tile(const float* __restrict__ src, int K, int N, bf16_t* __restrict__ dst, int ldd, int koff, int mode, int tile) {
;     float* scr = (float*)smem;
;     const int ntn = N / 128, kb = tile / ntn, nb = tile % ntn, k0 = kb * 64, n0 = nb * 128, tid = threadIdx.x;
;     f32x4 v[4];
; #pragma unroll
;     for (int i = 0; i < 4; ++i) { const int idx = tid + 512 * i, kk = idx >> 5, n4 = idx & 31; v[i] = *(const f32x4*)(src + (size_t)(k0 + kk) * N + n0 + n4 * 4); }
; #pragma unroll
;     for (int i = 0; i < 4; ++i) { const int idx = tid + 512 * i, kk = idx >> 5, n4 = idx & 31;
; #pragma unroll
;         for (int c = 0; c < 4; ++c) scr[kk * 129 + n4 * 4 + c] = v[i][c]; }
;     __syncthreads();
; #pragma unroll
;     for (int i = 0; i < 2; ++i) {
;         const int o = tid + 512 * i, n = o >> 3, kc = (o & 7) * 8;
;         u32x4 w;
;         w.x = pk_bf16(scr[(kc + 0) * 129 + n], scr[(kc + 1) * 129 + n]); w.y = pk_bf16(scr[(kc + 2) * 129 + n], scr[(kc + 3) * 129 + n]);
;         w.z = pk_bf16(scr[(kc + 4) * 129 + n], scr[(kc + 5) * 129 + n]); w.w = pk_bf16(scr[(kc + 6) * 129 + n], scr[(kc + 7) * 129 + n]);
;         const int f = n0 + n;
;         const int drow = mode == 0 ? f : ((f >> 7) * 256 + (mode == 2 ? 128 : 0) + (f & 127));
;         *(u32x4*)(dst + (size_t)drow * ldd + koff + k0 + kc) = w;
;     }
;     __syncthreads();
; }
; __device__ __forceinline__ void phase0(const Params& p) {
;     ...
;             if (r < J6) { transpose_tile(p.in[23], DFF, D, (bf16_t*)(ws + WS_WD), DFF, 0, 0, r); continue; } r -= J6;
.LBB0_65:
	s_andn2_b64 vcc, exec, s[4:5]
	s_cbranch_vccnz .LBB0_67
	s_lshl_b32 s0, s11, 3
	s_and_b32 s0, s0, 0x7fc0
	s_add_i32 s0, s0, 0xac80
	s_and_b32 s4, s0, 0xffc0
	s_lshl_b32 s0, s11, 7
	s_and_b32 s5, s0, 0x380
	s_lshl_b32 s0, s5, 2
	v_or_b32_e32 v0, s4, v165
	v_lshl_add_u64 v[12:13], v[110:111], 0, s[0:1]
	v_lshlrev_b32_e32 v82, 12, v0
	v_or_b32_e32 v0, s4, v81
	v_lshl_add_u64 v[8:9], v[12:13], 0, v[82:83]
	v_lshlrev_b32_e32 v82, 12, v0
	v_lshl_add_u64 v[10:11], v[12:13], 0, v[82:83]
	global_load_dwordx4 v[0:3], v[8:9], off nt
	global_load_dwordx4 v[4:7], v[10:11], off nt
	v_or_b32_e32 v8, s4, v158
	v_lshlrev_b32_e32 v82, 12, v8
	v_lshl_add_u64 v[8:9], v[12:13], 0, v[82:83]
	global_load_dwordx4 v[8:11], v[8:9], off nt
	v_add_lshl_u32 v82, v127, s4, 12
	v_lshl_add_u64 v[12:13], v[12:13], 0, v[82:83]
	global_load_dwordx4 v[12:15], v[12:13], off nt
	v_add_u32_e32 v20, v129, v159
	v_add_u32_e32 v21, v129, v160
	v_add_u32_e32 v22, v129, v161
	v_add_u32_e32 v23, 0x400, v131
	v_add_u32_e32 v24, 0x800, v131
	v_add_u32_e32 v25, 0xc00, v131
	v_add_u32_e32 v26, 0x400, v152
	v_add_u32_e32 v27, 0x800, v152
	v_add_u32_e32 v28, 0xc00, v152
	v_add_u32_e32 v29, 0x4080, v20
	v_add_u32_e32 v30, 0x4088, v20
	v_or_b32_e32 v16, s5, v153
	v_add_u32_e32 v17, s5, v135
	v_mul_u32_u24_e32 v18, 0xb00, v16
	s_lshl_b32 s0, s4, 1
	v_mul_u32_u24_e32 v31, 0xb00, v17
	v_lshl_add_u64 v[16:17], v[92:93], 0, s[0:1]
	v_lshlrev_b32_e32 v82, 1, v18
	v_lshl_add_u64 v[18:19], v[16:17], 0, v[82:83]
	v_lshlrev_b32_e32 v82, 1, v31
	v_lshl_add_u64 v[16:17], v[16:17], 0, v[82:83]
	s_waitcnt vmcnt(3)
	ds_write2_b32 v20, v0, v1 offset1:1
	ds_write2_b32 v20, v2, v3 offset0:2 offset1:3
	s_waitcnt vmcnt(2)
	ds_write2_b32 v21, v4, v5 offset1:1
	ds_write2_b32 v21, v6, v7 offset0:2 offset1:3
	s_waitcnt vmcnt(1)
	ds_write2_b32 v29, v8, v9 offset1:1
	ds_write2_b32 v30, v10, v11 offset1:1
	s_waitcnt vmcnt(0)
	ds_write2_b32 v22, v12, v13 offset1:1
	ds_write2_b32 v22, v14, v15 offset0:2 offset1:3
	s_waitcnt lgkmcnt(0)
	s_barrier
	ds_read2_b32 v[0:1], v131 offset1:129
	ds_read2_b32 v[2:3], v23 offset0:2 offset1:131
	ds_read2_b32 v[4:5], v24 offset0:4 offset1:133
	ds_read2_b32 v[6:7], v25 offset0:6 offset1:135
	ds_read2_b32 v[8:9], v152 offset1:129
	ds_read2_b32 v[10:11], v26 offset0:2 offset1:131
	ds_read2_b32 v[12:13], v27 offset0:4 offset1:133
	ds_read2_b32 v[14:15], v28 offset0:6 offset1:135
	s_waitcnt lgkmcnt(7)
	v_cvt_pk_bf16_f32 v0, v0, v1
	s_waitcnt lgkmcnt(6)
	v_cvt_pk_bf16_f32 v1, v2, v3
	s_waitcnt lgkmcnt(5)
	v_cvt_pk_bf16_f32 v2, v4, v5
	s_waitcnt lgkmcnt(4)
	v_cvt_pk_bf16_f32 v3, v6, v7
	s_waitcnt lgkmcnt(3)
	v_cvt_pk_bf16_f32 v4, v8, v9
	s_waitcnt lgkmcnt(2)
	v_cvt_pk_bf16_f32 v5, v10, v11
	s_waitcnt lgkmcnt(1)
	v_cvt_pk_bf16_f32 v6, v12, v13
	s_waitcnt lgkmcnt(0)
	v_cvt_pk_bf16_f32 v7, v14, v15
	global_store_dwordx4 v[18:19], v[0:3], off
	global_store_dwordx4 v[16:17], v[4:7], off
	s_barrier

; __device__ __forceinline__ unsigned pk_bf16(float lo, float hi) { const f32x2 v = {lo, hi}; return __builtin_bit_cast(unsigned, __builtin_convertvector(v, b16x2)); }
; __device__ __forceinline__ void transpose_tile(const float* __restrict__ src, int K, int N, bf16_t* __restrict__ dst, int ldd, int koff, int mode, int tile) {
;     float* scr = (float*)smem;
;     const int ntn = N / 128, kb = tile / ntn, nb = tile % ntn, k0 = kb * 64, n0 = nb * 128, tid = threadIdx.x;
;     f32x4 v[4];
; #pragma unroll
;     for (int i = 0; i < 4; ++i) { const int idx = tid + 512 * i, kk = idx >> 5, n4 = idx & 31; v[i] = *(const f32x4*)(src + (size_t)(k0 + kk) * N + n0 + n4 * 4); }
; #pragma unroll
;     for (int i = 0; i < 4; ++i) { const int idx = tid + 512 * i, kk = idx >> 5, n4 = idx & 31;
; #pragma unroll
;         for (int c = 0; c < 4; ++c) scr[kk * 129 + n4 * 4 + c] = v[i][c]; }
;     __syncthreads();
; #pragma unroll
;     for (int i = 0; i < 2; ++i) {
;         const int o = tid + 512 * i, n = o >> 3, kc = (o & 7) * 8;
;         u32x4 w;
;         w.x = pk_bf16(scr[(kc + 0) * 129 + n], scr[(kc + 1) * 129 + n]); w.y = pk_bf16(scr[(kc + 2) * 129 + n], scr[(kc + 3) * 129 + n]);
;         w.z = pk_bf16(scr[(kc + 4) * 129 + n], scr[(kc + 5) * 129 + n]); w.w = pk_bf16(scr[(kc + 6) * 129 + n], scr[(kc + 7) * 129 + n]);
;         const int f = n0 + n;
;         const int drow = mode == 0 ? f : ((f >> 7) * 256 + (mode == 2 ? 128 : 0) + (f & 127));
;         *(u32x4*)(dst + (size_t)drow * ldd + koff + k0 + kc) = w;
;     }
;     __syncthreads();
; }
; __device__ __forceinline__ void phase0(const Params& p) {
;     ...
;             if (r < J4) { transpose_tile(p.in[22], D, DFF, (bf16_t*)(ws + WS_WGU), D, 0, 2, r); continue; } r -= J4;
.LBB0_68:
	s_andn2_b64 vcc, exec, s[4:5]
	s_cbranch_vccnz .LBB0_70
	s_add_i32 s0, s11, 0xf6f0
	s_and_b32 s4, s0, 0xffff
	s_mul_i32 s4, s4, 0xba2f
	s_lshr_b32 s5, s4, 20
	s_mul_i32 s5, s5, 22
	s_lshr_b32 s4, s4, 14
	s_sub_i32 s0, s0, s5
	s_and_b32 s4, s4, 0xffc0
	s_lshl_b32 s0, s0, 7
	v_or_b32_e32 v0, s4, v165
	s_and_b32 s5, s0, 0xff80
	v_mul_u32_u24_e32 v0, 0xb00, v0
	s_lshl_b32 s0, s5, 2
	v_lshlrev_b32_e32 v82, 2, v0
	v_or_b32_e32 v0, s4, v81
	v_lshl_add_u64 v[12:13], v[112:113], 0, s[0:1]
	v_mul_u32_u24_e32 v0, 0xb00, v0
	v_lshl_add_u64 v[8:9], v[12:13], 0, v[82:83]
	v_lshlrev_b32_e32 v82, 2, v0
	v_lshl_add_u64 v[10:11], v[12:13], 0, v[82:83]
	global_load_dwordx4 v[0:3], v[8:9], off nt
	global_load_dwordx4 v[4:7], v[10:11], off nt
	v_or_b32_e32 v8, s4, v158
	v_mul_u32_u24_e32 v8, 0xb00, v8
	v_lshlrev_b32_e32 v82, 2, v8
	v_add_u32_e32 v14, s4, v127
	v_lshl_add_u64 v[8:9], v[12:13], 0, v[82:83]
	v_mul_u32_u24_e32 v14, 0xb00, v14
	global_load_dwordx4 v[8:11], v[8:9], off nt
	v_lshlrev_b32_e32 v82, 2, v14
	v_lshl_add_u64 v[12:13], v[12:13], 0, v[82:83]
	global_load_dwordx4 v[12:15], v[12:13], off nt
	v_add_u32_e32 v20, v129, v159
	v_add_u32_e32 v21, v129, v160
	v_add_u32_e32 v22, v129, v161
	v_add_u32_e32 v23, 0x400, v131
	v_add_u32_e32 v24, 0x800, v131
	v_add_u32_e32 v25, 0xc00, v131
	v_add_u32_e32 v26, 0x400, v152
	v_add_u32_e32 v27, 0x800, v152
	v_add_u32_e32 v28, 0xc00, v152
	v_add_u32_e32 v29, 0x4080, v20
	v_add_u32_e32 v30, 0x4088, v20
	v_add_lshl_u32 v16, v135, s5, 1
	s_lshl_b32 s0, s4, 1
	v_and_or_b32 v31, v16, s10, v135
	v_lshl_add_u64 v[16:17], v[94:95], 0, s[0:1]
	v_lshl_or_b32 v82, s5, 12, v157
	v_lshl_add_u64 v[18:19], v[16:17], 0, v[82:83]
	v_lshl_or_b32 v82, v31, 11, v163
	v_lshl_add_u64 v[16:17], v[16:17], 0, v[82:83]
	s_waitcnt vmcnt(3)
	ds_write2_b32 v20, v0, v1 offset1:1
	ds_write2_b32 v20, v2, v3 offset0:2 offset1:3
	s_waitcnt vmcnt(2)
	ds_write2_b32 v21, v4, v5 offset1:1
	ds_write2_b32 v21, v6, v7 offset0:2 offset1:3
	s_waitcnt vmcnt(1)
	ds_write2_b32 v29, v8, v9 offset1:1
	ds_write2_b32 v30, v10, v11 offset1:1
	s_waitcnt vmcnt(0)
	ds_write2_b32 v22, v12, v13 offset1:1
	ds_write2_b32 v22, v14, v15 offset0:2 offset1:3
	s_waitcnt lgkmcnt(0)
	s_barrier
	ds_read2_b32 v[0:1], v131 offset1:129
	ds_read2_b32 v[2:3], v23 offset0:2 offset1:131
	ds_read2_b32 v[4:5], v24 offset0:4 offset1:133
	ds_read2_b32 v[6:7], v25 offset0:6 offset1:135
	ds_read2_b32 v[8:9], v152 offset1:129
	ds_read2_b32 v[10:11], v26 offset0:2 offset1:131
	ds_read2_b32 v[12:13], v27 offset0:4 offset1:133
	ds_read2_b32 v[14:15], v28 offset0:6 offset1:135
	s_waitcnt lgkmcnt(7)
	v_cvt_pk_bf16_f32 v0, v0, v1
	s_waitcnt lgkmcnt(6)
	v_cvt_pk_bf16_f32 v1, v2, v3
	s_waitcnt lgkmcnt(5)
	v_cvt_pk_bf16_f32 v2, v4, v5
	s_waitcnt lgkmcnt(4)
	v_cvt_pk_bf16_f32 v3, v6, v7
	s_waitcnt lgkmcnt(3)
	v_cvt_pk_bf16_f32 v4, v8, v9
	s_waitcnt lgkmcnt(2)
	v_cvt_pk_bf16_f32 v5, v10, v11
	s_waitcnt lgkmcnt(1)
	v_cvt_pk_bf16_f32 v6, v12, v13
	s_waitcnt lgkmcnt(0)
	v_cvt_pk_bf16_f32 v7, v14, v15
	global_store_dwordx4 v[18:19], v[0:3], off
	global_store_dwordx4 v[16:17], v[4:7], off
	s_barrier

; __device__ __forceinline__ unsigned pk_bf16(float lo, float hi) { const f32x2 v = {lo, hi}; return __builtin_bit_cast(unsigned, __builtin_convertvector(v, b16x2)); }
; __device__ __forceinline__ void transpose_tile(const float* __restrict__ src, int K, int N, bf16_t* __restrict__ dst, int ldd, int koff, int mode, int tile) {
;     float* scr = (float*)smem;
;     const int ntn = N / 128, kb = tile / ntn, nb = tile % ntn, k0 = kb * 64, n0 = nb * 128, tid = threadIdx.x;
;     f32x4 v[4];
; #pragma unroll
;     for (int i = 0; i < 4; ++i) { const int idx = tid + 512 * i, kk = idx >> 5, n4 = idx & 31; v[i] = *(const f32x4*)(src + (size_t)(k0 + kk) * N + n0 + n4 * 4); }
; #pragma unroll
;     for (int i = 0; i < 4; ++i) { const int idx = tid + 512 * i, kk = idx >> 5, n4 = idx & 31;
; #pragma unroll
;         for (int c = 0; c < 4; ++c) scr[kk * 129 + n4 * 4 + c] = v[i][c]; }
;     __syncthreads();
; #pragma unroll
;     for (int i = 0; i < 2; ++i) {
;         const int o = tid + 512 * i, n = o >> 3, kc = (o & 7) * 8;
;         u32x4 w;
;         w.x = pk_bf16(scr[(kc + 0) * 129 + n], scr[(kc + 1) * 129 + n]); w.y = pk_bf16(scr[(kc + 2) * 129 + n], scr[(kc + 3) * 129 + n]);
;         w.z = pk_bf16(scr[(kc + 4) * 129 + n], scr[(kc + 5) * 129 + n]); w.w = pk_bf16(scr[(kc + 6) * 129 + n], scr[(kc + 7) * 129 + n]);
;         const int f = n0 + n;
;         const int drow = mode == 0 ? f : ((f >> 7) * 256 + (mode == 2 ? 128 : 0) + (f & 127));
;         *(u32x4*)(dst + (size_t)drow * ldd + koff + k0 + kc) = w;
;     }
;     __syncthreads();
; }
; __device__ __forceinline__ void phase0(const Params& p) {
;     ...
;             if (r < J4) { transpose_tile(p.in[21], D, DFF, (bf16_t*)(ws + WS_WGU), D, 0, 1, r); continue; } r -= J4;
.LBB0_71:
	s_andn2_b64 vcc, exec, s[4:5]
	s_cbranch_vccnz .LBB0_73
	s_add_i32 s0, s11, 0xf850
	s_and_b32 s4, s0, 0xffff
	s_mul_i32 s4, s4, 0xba2f
	s_lshr_b32 s5, s4, 20
	s_mul_i32 s5, s5, 22
	s_lshr_b32 s4, s4, 14
	s_sub_i32 s0, s0, s5
	s_and_b32 s4, s4, 0xffc0
	s_lshl_b32 s0, s0, 7
	v_or_b32_e32 v0, s4, v165
	s_and_b32 s5, s0, 0xff80
	v_mul_u32_u24_e32 v0, 0xb00, v0
	s_lshl_b32 s0, s5, 2
	v_lshlrev_b32_e32 v82, 2, v0
	v_or_b32_e32 v0, s4, v81
	v_lshl_add_u64 v[12:13], v[114:115], 0, s[0:1]
	v_mul_u32_u24_e32 v0, 0xb00, v0
	v_lshl_add_u64 v[8:9], v[12:13], 0, v[82:83]
	v_lshlrev_b32_e32 v82, 2, v0
	v_lshl_add_u64 v[10:11], v[12:13], 0, v[82:83]
	global_load_dwordx4 v[0:3], v[8:9], off nt
	global_load_dwordx4 v[4:7], v[10:11], off nt
	v_or_b32_e32 v8, s4, v158
	v_mul_u32_u24_e32 v8, 0xb00, v8
	v_lshlrev_b32_e32 v82, 2, v8
	v_add_u32_e32 v14, s4, v127
	v_lshl_add_u64 v[8:9], v[12:13], 0, v[82:83]
	v_mul_u32_u24_e32 v14, 0xb00, v14
	global_load_dwordx4 v[8:11], v[8:9], off nt
	v_lshlrev_b32_e32 v82, 2, v14
	v_lshl_add_u64 v[12:13], v[12:13], 0, v[82:83]
	global_load_dwordx4 v[12:15], v[12:13], off nt
	v_add_u32_e32 v20, v129, v159
	v_add_u32_e32 v21, v129, v160
	v_add_u32_e32 v22, v129, v161
	v_add_u32_e32 v23, 0x400, v131
	v_add_u32_e32 v24, 0x800, v131
	v_add_u32_e32 v25, 0xc00, v131
	v_add_u32_e32 v26, 0x400, v152
	v_add_u32_e32 v27, 0x800, v152
	v_add_u32_e32 v28, 0xc00, v152
	v_add_u32_e32 v29, 0x4080, v20
	v_add_u32_e32 v30, 0x4088, v20
	v_lshlrev_b32_e32 v18, 1, v154
	v_add_lshl_u32 v16, v135, s5, 1
	s_lshl_b32 s0, s4, 1
	v_and_or_b32 v31, v16, s10, v155
	v_lshl_add_u64 v[16:17], v[94:95], 0, s[0:1]
	v_lshl_or_b32 v82, s5, 12, v18
	v_lshl_add_u64 v[18:19], v[16:17], 0, v[82:83]
	v_lshlrev_b32_e32 v82, 11, v31
	v_lshl_add_u64 v[16:17], v[16:17], 0, v[82:83]
	s_waitcnt vmcnt(3)
	ds_write2_b32 v20, v0, v1 offset1:1
	ds_write2_b32 v20, v2, v3 offset0:2 offset1:3
	s_waitcnt vmcnt(2)
	ds_write2_b32 v21, v4, v5 offset1:1
	ds_write2_b32 v21, v6, v7 offset0:2 offset1:3
	s_waitcnt vmcnt(1)
	ds_write2_b32 v29, v8, v9 offset1:1
	ds_write2_b32 v30, v10, v11 offset1:1
	s_waitcnt vmcnt(0)
	ds_write2_b32 v22, v12, v13 offset1:1
	ds_write2_b32 v22, v14, v15 offset0:2 offset1:3
	s_waitcnt lgkmcnt(0)
	s_barrier
	ds_read2_b32 v[0:1], v131 offset1:129
	ds_read2_b32 v[2:3], v23 offset0:2 offset1:131
	ds_read2_b32 v[4:5], v24 offset0:4 offset1:133
	ds_read2_b32 v[6:7], v25 offset0:6 offset1:135
	ds_read2_b32 v[8:9], v152 offset1:129
	ds_read2_b32 v[10:11], v26 offset0:2 offset1:131
	ds_read2_b32 v[12:13], v27 offset0:4 offset1:133
	ds_read2_b32 v[14:15], v28 offset0:6 offset1:135
	s_waitcnt lgkmcnt(7)
	v_cvt_pk_bf16_f32 v0, v0, v1
	s_waitcnt lgkmcnt(6)
	v_cvt_pk_bf16_f32 v1, v2, v3
	s_waitcnt lgkmcnt(5)
	v_cvt_pk_bf16_f32 v2, v4, v5
	s_waitcnt lgkmcnt(4)
	v_cvt_pk_bf16_f32 v3, v6, v7
	s_waitcnt lgkmcnt(3)
	v_cvt_pk_bf16_f32 v4, v8, v9
	s_waitcnt lgkmcnt(2)
	v_cvt_pk_bf16_f32 v5, v10, v11
	s_waitcnt lgkmcnt(1)
	v_cvt_pk_bf16_f32 v6, v12, v13
	s_waitcnt lgkmcnt(0)
	v_cvt_pk_bf16_f32 v7, v14, v15
	global_store_dwordx4 v[18:19], v[0:3], off
	global_store_dwordx4 v[16:17], v[4:7], off
	s_barrier

; __device__ __forceinline__ unsigned pk_bf16(float lo, float hi) { const f32x2 v = {lo, hi}; return __builtin_bit_cast(unsigned, __builtin_convertvector(v, b16x2)); }
; __device__ __forceinline__ void transpose_tile(const float* __restrict__ src, int K, int N, bf16_t* __restrict__ dst, int ldd, int koff, int mode, int tile) {
;     float* scr = (float*)smem;
;     const int ntn = N / 128, kb = tile / ntn, nb = tile % ntn, k0 = kb * 64, n0 = nb * 128, tid = threadIdx.x;
;     f32x4 v[4];
; #pragma unroll
;     for (int i = 0; i < 4; ++i) { const int idx = tid + 512 * i, kk = idx >> 5, n4 = idx & 31; v[i] = *(const f32x4*)(src + (size_t)(k0 + kk) * N + n0 + n4 * 4); }
; #pragma unroll
;     for (int i = 0; i < 4; ++i) { const int idx = tid + 512 * i, kk = idx >> 5, n4 = idx & 31;
; #pragma unroll
;         for (int c = 0; c < 4; ++c) scr[kk * 129 + n4 * 4 + c] = v[i][c]; }
;     __syncthreads();
; #pragma unroll
;     for (int i = 0; i < 2; ++i) {
;         const int o = tid + 512 * i, n = o >> 3, kc = (o & 7) * 8;
;         u32x4 w;
;         w.x = pk_bf16(scr[(kc + 0) * 129 + n], scr[(kc + 1) * 129 + n]); w.y = pk_bf16(scr[(kc + 2) * 129 + n], scr[(kc + 3) * 129 + n]);
;         w.z = pk_bf16(scr[(kc + 4) * 129 + n], scr[(kc + 5) * 129 + n]); w.w = pk_bf16(scr[(kc + 6) * 129 + n], scr[(kc + 7) * 129 + n]);
;         const int f = n0 + n;
;         const int drow = mode == 0 ? f : ((f >> 7) * 256 + (mode == 2 ? 128 : 0) + (f & 127));
;         *(u32x4*)(dst + (size_t)drow * ldd + koff + k0 + kc) = w;
;     }
;     __syncthreads();
; }
; __device__ __forceinline__ void phase0(const Params& p) {
;     ...
;             if (r < J3) { transpose_tile(p.in[18], D, D, (bf16_t*)(ws + WS_WOUT), D, 0, 0, r); continue; } r -= J3;
.LBB0_74:
	s_andn2_b64 vcc, exec, s[4:5]
	s_cbranch_vccnz .LBB0_76
	s_lshl_b32 s0, s11, 3
	s_add_i32 s0, s0, 0x7fe80
	s_and_b32 s4, s0, 0x7c0
	s_lshl_b32 s0, s11, 7
	s_and_b32 s5, s0, 0x380
	s_lshl_b32 s0, s5, 2
	v_or_b32_e32 v0, s4, v165
	v_lshl_add_u64 v[12:13], v[116:117], 0, s[0:1]
	v_lshlrev_b32_e32 v82, 12, v0
	v_or_b32_e32 v0, s4, v81
	v_lshl_add_u64 v[8:9], v[12:13], 0, v[82:83]
	v_lshlrev_b32_e32 v82, 12, v0
	v_lshl_add_u64 v[10:11], v[12:13], 0, v[82:83]
	global_load_dwordx4 v[0:3], v[8:9], off nt
	global_load_dwordx4 v[4:7], v[10:11], off nt
	v_or_b32_e32 v8, s4, v158
	v_lshlrev_b32_e32 v82, 12, v8
	v_lshl_add_u64 v[8:9], v[12:13], 0, v[82:83]
	global_load_dwordx4 v[8:11], v[8:9], off nt
	v_add_lshl_u32 v82, v127, s4, 12
	v_lshl_add_u64 v[12:13], v[12:13], 0, v[82:83]
	global_load_dwordx4 v[12:15], v[12:13], off nt
	v_add_u32_e32 v20, v129, v159
	v_add_u32_e32 v21, v129, v160
	v_add_u32_e32 v22, v129, v161
	v_add_u32_e32 v23, 0x400, v131
	v_add_u32_e32 v24, 0x800, v131
	v_add_u32_e32 v25, 0xc00, v131
	v_add_u32_e32 v26, 0x400, v152
	v_add_u32_e32 v27, 0x800, v152
	v_add_u32_e32 v28, 0xc00, v152
	v_add_u32_e32 v29, 0x4080, v20
	v_add_u32_e32 v30, 0x4088, v20
	v_or_b32_e32 v18, s5, v153
	s_lshl_b32 s0, s4, 1
	v_lshl_add_u64 v[16:17], v[96:97], 0, s[0:1]
	v_lshlrev_b32_e32 v82, 11, v18
	v_lshl_add_u64 v[18:19], v[16:17], 0, v[82:83]
	v_add_lshl_u32 v82, v135, s5, 11
	v_lshl_add_u64 v[16:17], v[16:17], 0, v[82:83]
	s_waitcnt vmcnt(3)
	ds_write2_b32 v20, v0, v1 offset1:1
	ds_write2_b32 v20, v2, v3 offset0:2 offset1:3
	s_waitcnt vmcnt(2)
	ds_write2_b32 v21, v4, v5 offset1:1
	ds_write2_b32 v21, v6, v7 offset0:2 offset1:3
	s_waitcnt vmcnt(1)
	ds_write2_b32 v29, v8, v9 offset1:1
	ds_write2_b32 v30, v10, v11 offset1:1
	s_waitcnt vmcnt(0)
	ds_write2_b32 v22, v12, v13 offset1:1
	ds_write2_b32 v22, v14, v15 offset0:2 offset1:3
	s_waitcnt lgkmcnt(0)
	s_barrier
	ds_read2_b32 v[0:1], v131 offset1:129
	ds_read2_b32 v[2:3], v23 offset0:2 offset1:131
	ds_read2_b32 v[4:5], v24 offset0:4 offset1:133
	ds_read2_b32 v[6:7], v25 offset0:6 offset1:135
	ds_read2_b32 v[8:9], v152 offset1:129
	ds_read2_b32 v[10:11], v26 offset0:2 offset1:131
	ds_read2_b32 v[12:13], v27 offset0:4 offset1:133
	ds_read2_b32 v[14:15], v28 offset0:6 offset1:135
	s_waitcnt lgkmcnt(7)
	v_cvt_pk_bf16_f32 v0, v0, v1
	s_waitcnt lgkmcnt(6)
	v_cvt_pk_bf16_f32 v1, v2, v3
	s_waitcnt lgkmcnt(5)
	v_cvt_pk_bf16_f32 v2, v4, v5
	s_waitcnt lgkmcnt(4)
	v_cvt_pk_bf16_f32 v3, v6, v7
	s_waitcnt lgkmcnt(3)
	v_cvt_pk_bf16_f32 v4, v8, v9
	s_waitcnt lgkmcnt(2)
	v_cvt_pk_bf16_f32 v5, v10, v11
	s_waitcnt lgkmcnt(1)
	v_cvt_pk_bf16_f32 v6, v12, v13
	s_waitcnt lgkmcnt(0)
	v_cvt_pk_bf16_f32 v7, v14, v15
	global_store_dwordx4 v[18:19], v[0:3], off
	global_store_dwordx4 v[16:17], v[4:7], off
	s_barrier

; __device__ __forceinline__ unsigned pk_bf16(float lo, float hi) { const f32x2 v = {lo, hi}; return __builtin_bit_cast(unsigned, __builtin_convertvector(v, b16x2)); }
; __device__ __forceinline__ void transpose_tile(const float* __restrict__ src, int K, int N, bf16_t* __restrict__ dst, int ldd, int koff, int mode, int tile) {
;     float* scr = (float*)smem;
;     const int ntn = N / 128, kb = tile / ntn, nb = tile % ntn, k0 = kb * 64, n0 = nb * 128, tid = threadIdx.x;
;     f32x4 v[4];
; #pragma unroll
;     for (int i = 0; i < 4; ++i) { const int idx = tid + 512 * i, kk = idx >> 5, n4 = idx & 31; v[i] = *(const f32x4*)(src + (size_t)(k0 + kk) * N + n0 + n4 * 4); }
; #pragma unroll
;     for (int i = 0; i < 4; ++i) { const int idx = tid + 512 * i, kk = idx >> 5, n4 = idx & 31;
; #pragma unroll
;         for (int c = 0; c < 4; ++c) scr[kk * 129 + n4 * 4 + c] = v[i][c]; }
;     __syncthreads();
; #pragma unroll
;     for (int i = 0; i < 2; ++i) {
;         const int o = tid + 512 * i, n = o >> 3, kc = (o & 7) * 8;
;         u32x4 w;
;         w.x = pk_bf16(scr[(kc + 0) * 129 + n], scr[(kc + 1) * 129 + n]); w.y = pk_bf16(scr[(kc + 2) * 129 + n], scr[(kc + 3) * 129 + n]);
;         w.z = pk_bf16(scr[(kc + 4) * 129 + n], scr[(kc + 5) * 129 + n]); w.w = pk_bf16(scr[(kc + 6) * 129 + n], scr[(kc + 7) * 129 + n]);
;         const int f = n0 + n;
;         const int drow = mode == 0 ? f : ((f >> 7) * 256 + (mode == 2 ? 128 : 0) + (f & 127));
;         *(u32x4*)(dst + (size_t)drow * ldd + koff + k0 + kc) = w;
;     }
;     __syncthreads();
; }
; __device__ __forceinline__ void phase0(const Params& p) {
;     ...
;             if (r < J1) { transpose_tile(p.in[17], 512, D, (bf16_t*)(ws + WS_WRW), 512, 0, 0, r); continue; } r -= J1;
.LBB0_77:
	s_andn2_b64 vcc, exec, s[4:5]
	s_cbranch_vccnz .LBB0_79
	s_lshl_b32 s0, s11, 3
	s_addk_i32 s0, 0x80
	s_and_b32 s4, s0, 0x7c0
	s_lshl_b32 s0, s11, 7
	s_and_b32 s5, s0, 0x380
	s_lshl_b32 s0, s5, 2
	v_or_b32_e32 v0, s4, v165
	v_lshl_add_u64 v[12:13], v[118:119], 0, s[0:1]
	v_lshlrev_b32_e32 v82, 12, v0
	v_or_b32_e32 v0, s4, v81
	v_lshl_add_u64 v[8:9], v[12:13], 0, v[82:83]
	v_lshlrev_b32_e32 v82, 12, v0
	v_lshl_add_u64 v[10:11], v[12:13], 0, v[82:83]
	global_load_dwordx4 v[0:3], v[8:9], off nt
	global_load_dwordx4 v[4:7], v[10:11], off nt
	v_or_b32_e32 v8, s4, v158
	v_lshlrev_b32_e32 v82, 12, v8
	v_lshl_add_u64 v[8:9], v[12:13], 0, v[82:83]
	global_load_dwordx4 v[8:11], v[8:9], off nt
	v_add_lshl_u32 v82, v127, s4, 12
	v_lshl_add_u64 v[12:13], v[12:13], 0, v[82:83]
	global_load_dwordx4 v[12:15], v[12:13], off nt
	v_add_u32_e32 v20, v129, v159
	v_add_u32_e32 v21, v129, v160
	v_add_u32_e32 v22, v129, v161
	v_add_u32_e32 v23, 0x400, v131
	v_add_u32_e32 v24, 0x800, v131
	v_add_u32_e32 v25, 0xc00, v131
	v_add_u32_e32 v26, 0x400, v152
	v_add_u32_e32 v27, 0x800, v152
	v_add_u32_e32 v28, 0xc00, v152
	v_add_u32_e32 v29, 0x4080, v20
	v_add_u32_e32 v30, 0x4088, v20
	v_or_b32_e32 v18, s5, v153
	s_lshl_b32 s0, s4, 1
	v_lshl_add_u64 v[16:17], v[98:99], 0, s[0:1]
	v_lshlrev_b32_e32 v82, 10, v18
	v_lshl_add_u64 v[18:19], v[16:17], 0, v[82:83]
	v_add_lshl_u32 v82, v135, s5, 10
	v_lshl_add_u64 v[16:17], v[16:17], 0, v[82:83]
	s_waitcnt vmcnt(3)
	ds_write2_b32 v20, v0, v1 offset1:1
	ds_write2_b32 v20, v2, v3 offset0:2 offset1:3
	s_waitcnt vmcnt(2)
	ds_write2_b32 v21, v4, v5 offset1:1
	ds_write2_b32 v21, v6, v7 offset0:2 offset1:3
	s_waitcnt vmcnt(1)
	ds_write2_b32 v29, v8, v9 offset1:1
	ds_write2_b32 v30, v10, v11 offset1:1
	s_waitcnt vmcnt(0)
	ds_write2_b32 v22, v12, v13 offset1:1
	ds_write2_b32 v22, v14, v15 offset0:2 offset1:3
	s_waitcnt lgkmcnt(0)
	s_barrier
	ds_read2_b32 v[0:1], v131 offset1:129
	ds_read2_b32 v[2:3], v23 offset0:2 offset1:131
	ds_read2_b32 v[4:5], v24 offset0:4 offset1:133
	ds_read2_b32 v[6:7], v25 offset0:6 offset1:135
	ds_read2_b32 v[8:9], v152 offset1:129
	ds_read2_b32 v[10:11], v26 offset0:2 offset1:131
	ds_read2_b32 v[12:13], v27 offset0:4 offset1:133
	ds_read2_b32 v[14:15], v28 offset0:6 offset1:135
	s_waitcnt lgkmcnt(7)
	v_cvt_pk_bf16_f32 v0, v0, v1
	s_waitcnt lgkmcnt(6)
	v_cvt_pk_bf16_f32 v1, v2, v3
	s_waitcnt lgkmcnt(5)
	v_cvt_pk_bf16_f32 v2, v4, v5
	s_waitcnt lgkmcnt(4)
	v_cvt_pk_bf16_f32 v3, v6, v7
	s_waitcnt lgkmcnt(3)
	v_cvt_pk_bf16_f32 v4, v8, v9
	s_waitcnt lgkmcnt(2)
	v_cvt_pk_bf16_f32 v5, v10, v11
	s_waitcnt lgkmcnt(1)
	v_cvt_pk_bf16_f32 v6, v12, v13
	s_waitcnt lgkmcnt(0)
	v_cvt_pk_bf16_f32 v7, v14, v15
	global_store_dwordx4 v[18:19], v[0:3], off
	global_store_dwordx4 v[16:17], v[4:7], off
	s_barrier

; __device__ __forceinline__ unsigned pk_bf16(float lo, float hi) { const f32x2 v = {lo, hi}; return __builtin_bit_cast(unsigned, __builtin_convertvector(v, b16x2)); }
; __device__ __forceinline__ void transpose_tile(const float* __restrict__ src, int K, int N, bf16_t* __restrict__ dst, int ldd, int koff, int mode, int tile) {
;     float* scr = (float*)smem;
;     const int ntn = N / 128, kb = tile / ntn, nb = tile % ntn, k0 = kb * 64, n0 = nb * 128, tid = threadIdx.x;
;     f32x4 v[4];
; #pragma unroll
;     for (int i = 0; i < 4; ++i) { const int idx = tid + 512 * i, kk = idx >> 5, n4 = idx & 31; v[i] = *(const f32x4*)(src + (size_t)(k0 + kk) * N + n0 + n4 * 4); }
; #pragma unroll
;     for (int i = 0; i < 4; ++i) { const int idx = tid + 512 * i, kk = idx >> 5, n4 = idx & 31;
; #pragma unroll
;         for (int c = 0; c < 4; ++c) scr[kk * 129 + n4 * 4 + c] = v[i][c]; }
;     __syncthreads();
; #pragma unroll
;     for (int i = 0; i < 2; ++i) {
;         const int o = tid + 512 * i, n = o >> 3, kc = (o & 7) * 8;
;         u32x4 w;
;         w.x = pk_bf16(scr[(kc + 0) * 129 + n], scr[(kc + 1) * 129 + n]); w.y = pk_bf16(scr[(kc + 2) * 129 + n], scr[(kc + 3) * 129 + n]);
;         w.z = pk_bf16(scr[(kc + 4) * 129 + n], scr[(kc + 5) * 129 + n]); w.w = pk_bf16(scr[(kc + 6) * 129 + n], scr[(kc + 7) * 129 + n]);
;         const int f = n0 + n;
;         const int drow = mode == 0 ? f : ((f >> 7) * 256 + (mode == 2 ? 128 : 0) + (f & 127));
;         *(u32x4*)(dst + (size_t)drow * ldd + koff + k0 + kc) = w;
;     }
;     __syncthreads();
; }
; __device__ __forceinline__ void phase0(const Params& p) {
;     ...
;             if (r < J1) { transpose_tile(p.in[16], 512, D, (bf16_t*)(ws + WS_WSB), 512, 0, 0, r); continue; } r -= J1;
.LBB0_80:
	s_andn2_b64 vcc, exec, s[4:5]
	s_cbranch_vccnz .LBB0_82
	s_lshl_b32 s0, s11, 3
	s_addk_i32 s0, 0x280
	s_and_b32 s4, s0, 0x7c0
	s_lshl_b32 s0, s11, 7
	s_and_b32 s5, s0, 0x380
	s_lshl_b32 s0, s5, 2
	v_or_b32_e32 v0, s4, v165
	v_lshl_add_u64 v[12:13], v[120:121], 0, s[0:1]
	v_lshlrev_b32_e32 v82, 12, v0
	v_or_b32_e32 v0, s4, v81
	v_lshl_add_u64 v[8:9], v[12:13], 0, v[82:83]
	v_lshlrev_b32_e32 v82, 12, v0
	v_lshl_add_u64 v[10:11], v[12:13], 0, v[82:83]
	global_load_dwordx4 v[0:3], v[8:9], off nt
	global_load_dwordx4 v[4:7], v[10:11], off nt
	v_or_b32_e32 v8, s4, v158
	v_lshlrev_b32_e32 v82, 12, v8
	v_lshl_add_u64 v[8:9], v[12:13], 0, v[82:83]
	global_load_dwordx4 v[8:11], v[8:9], off nt
	v_add_lshl_u32 v82, v127, s4, 12
	v_lshl_add_u64 v[12:13], v[12:13], 0, v[82:83]
	global_load_dwordx4 v[12:15], v[12:13], off nt
	v_add_u32_e32 v20, v129, v159
	v_add_u32_e32 v21, v129, v160
	v_add_u32_e32 v22, v129, v161
	v_add_u32_e32 v23, 0x400, v131
	v_add_u32_e32 v24, 0x800, v131
	v_add_u32_e32 v25, 0xc00, v131
	v_add_u32_e32 v26, 0x400, v152
	v_add_u32_e32 v27, 0x800, v152
	v_add_u32_e32 v28, 0xc00, v152
	v_add_u32_e32 v29, 0x4080, v20
	v_add_u32_e32 v30, 0x4088, v20
	v_or_b32_e32 v18, s5, v153
	s_lshl_b32 s0, s4, 1
	v_lshl_add_u64 v[16:17], v[100:101], 0, s[0:1]
	v_lshlrev_b32_e32 v82, 10, v18
	v_lshl_add_u64 v[18:19], v[16:17], 0, v[82:83]
	v_add_lshl_u32 v82, v135, s5, 10
	v_lshl_add_u64 v[16:17], v[16:17], 0, v[82:83]
	s_waitcnt vmcnt(3)
	ds_write2_b32 v20, v0, v1 offset1:1
	ds_write2_b32 v20, v2, v3 offset0:2 offset1:3
	s_waitcnt vmcnt(2)
	ds_write2_b32 v21, v4, v5 offset1:1
	ds_write2_b32 v21, v6, v7 offset0:2 offset1:3
	s_waitcnt vmcnt(1)
	ds_write2_b32 v29, v8, v9 offset1:1
	ds_write2_b32 v30, v10, v11 offset1:1
	s_waitcnt vmcnt(0)
	ds_write2_b32 v22, v12, v13 offset1:1
	ds_write2_b32 v22, v14, v15 offset0:2 offset1:3
	s_waitcnt lgkmcnt(0)
	s_barrier
	ds_read2_b32 v[0:1], v131 offset1:129
	ds_read2_b32 v[2:3], v23 offset0:2 offset1:131
	ds_read2_b32 v[4:5], v24 offset0:4 offset1:133
	ds_read2_b32 v[6:7], v25 offset0:6 offset1:135
	ds_read2_b32 v[8:9], v152 offset1:129
	ds_read2_b32 v[10:11], v26 offset0:2 offset1:131
	ds_read2_b32 v[12:13], v27 offset0:4 offset1:133
	ds_read2_b32 v[14:15], v28 offset0:6 offset1:135
	s_waitcnt lgkmcnt(7)
	v_cvt_pk_bf16_f32 v0, v0, v1
	s_waitcnt lgkmcnt(6)
	v_cvt_pk_bf16_f32 v1, v2, v3
	s_waitcnt lgkmcnt(5)
	v_cvt_pk_bf16_f32 v2, v4, v5
	s_waitcnt lgkmcnt(4)
	v_cvt_pk_bf16_f32 v3, v6, v7
	s_waitcnt lgkmcnt(3)
	v_cvt_pk_bf16_f32 v4, v8, v9
	s_waitcnt lgkmcnt(2)
	v_cvt_pk_bf16_f32 v5, v10, v11
	s_waitcnt lgkmcnt(1)
	v_cvt_pk_bf16_f32 v6, v12, v13
	s_waitcnt lgkmcnt(0)
	v_cvt_pk_bf16_f32 v7, v14, v15
	global_store_dwordx4 v[18:19], v[0:3], off
	global_store_dwordx4 v[16:17], v[4:7], off
	s_barrier

; __device__ __forceinline__ unsigned pk_bf16(float lo, float hi) { const f32x2 v = {lo, hi}; return __builtin_bit_cast(unsigned, __builtin_convertvector(v, b16x2)); }
; __device__ __forceinline__ void transpose_tile(const float* __restrict__ src, int K, int N, bf16_t* __restrict__ dst, int ldd, int koff, int mode, int tile) {
;     float* scr = (float*)smem;
;     const int ntn = N / 128, kb = tile / ntn, nb = tile % ntn, k0 = kb * 64, n0 = nb * 128, tid = threadIdx.x;
;     f32x4 v[4];
; #pragma unroll
;     for (int i = 0; i < 4; ++i) { const int idx = tid + 512 * i, kk = idx >> 5, n4 = idx & 31; v[i] = *(const f32x4*)(src + (size_t)(k0 + kk) * N + n0 + n4 * 4); }
; #pragma unroll
;     for (int i = 0; i < 4; ++i) { const int idx = tid + 512 * i, kk = idx >> 5, n4 = idx & 31;
; #pragma unroll
;         for (int c = 0; c < 4; ++c) scr[kk * 129 + n4 * 4 + c] = v[i][c]; }
;     __syncthreads();
; #pragma unroll
;     for (int i = 0; i < 2; ++i) {
;         const int o = tid + 512 * i, n = o >> 3, kc = (o & 7) * 8;
;         u32x4 w;
;         w.x = pk_bf16(scr[(kc + 0) * 129 + n], scr[(kc + 1) * 129 + n]); w.y = pk_bf16(scr[(kc + 2) * 129 + n], scr[(kc + 3) * 129 + n]);
;         w.z = pk_bf16(scr[(kc + 4) * 129 + n], scr[(kc + 5) * 129 + n]); w.w = pk_bf16(scr[(kc + 6) * 129 + n], scr[(kc + 7) * 129 + n]);
;         const int f = n0 + n;
;         const int drow = mode == 0 ? f : ((f >> 7) * 256 + (mode == 2 ? 128 : 0) + (f & 127));
;         *(u32x4*)(dst + (size_t)drow * ldd + koff + k0 + kc) = w;
;     }
;     __syncthreads();
; }
; __device__ __forceinline__ void phase0(const Params& p) {
;     ...
;             if (r < J0) { transpose_tile(p.in[4], D, PIN, (bf16_t*)(ws + WS_WIN), D, 0, 0, r); continue; } r -= J0;
.LBB0_83:
	s_andn2_b64 vcc, exec, s[4:5]
	s_cbranch_vccnz .LBB0_21
	s_add_i32 s0, s11, 0xfbf0
	s_bfe_u32 s4, s0, 0xf0001
	s_mul_i32 s4, s4, 0xc30d
	s_lshr_b32 s5, s4, 20
	s_mul_i32 s5, s5, 42
	s_lshr_b32 s4, s4, 14
	s_sub_i32 s0, s0, s5
	s_and_b32 s4, s4, 0xffc0
	s_lshl_b32 s0, s0, 7
	v_or_b32_e32 v0, s4, v165
	s_and_b32 s5, s0, 0xff80
	v_mul_u32_u24_e32 v0, 0x1500, v0
	s_lshl_b32 s0, s5, 2
	v_lshlrev_b32_e32 v82, 2, v0
	v_or_b32_e32 v0, s4, v81
	v_lshl_add_u64 v[12:13], v[122:123], 0, s[0:1]
	v_mul_u32_u24_e32 v0, 0x1500, v0
	v_lshl_add_u64 v[8:9], v[12:13], 0, v[82:83]
	v_lshlrev_b32_e32 v82, 2, v0
	v_lshl_add_u64 v[10:11], v[12:13], 0, v[82:83]
	global_load_dwordx4 v[0:3], v[8:9], off nt
	global_load_dwordx4 v[4:7], v[10:11], off nt
	v_or_b32_e32 v8, s4, v158
	v_mul_u32_u24_e32 v8, 0x1500, v8
	v_lshlrev_b32_e32 v82, 2, v8
	v_add_u32_e32 v14, s4, v127
	v_lshl_add_u64 v[8:9], v[12:13], 0, v[82:83]
	v_mul_u32_u24_e32 v14, 0x1500, v14
	global_load_dwordx4 v[8:11], v[8:9], off nt
	v_lshlrev_b32_e32 v82, 2, v14
	v_lshl_add_u64 v[12:13], v[12:13], 0, v[82:83]
	global_load_dwordx4 v[12:15], v[12:13], off nt
	v_add_u32_e32 v20, v129, v159
	v_add_u32_e32 v21, v129, v160
	v_add_u32_e32 v22, v129, v161
	v_add_u32_e32 v23, 0x400, v131
	v_add_u32_e32 v24, 0x800, v131
	v_add_u32_e32 v25, 0xc00, v131
	v_add_u32_e32 v26, 0x400, v152
	v_add_u32_e32 v27, 0x800, v152
	v_add_u32_e32 v28, 0xc00, v152
	v_add_u32_e32 v29, 0x4080, v20
	v_add_u32_e32 v30, 0x4088, v20
	v_or_b32_e32 v18, s5, v153
	s_lshl_b32 s0, s4, 1
	v_lshl_add_u64 v[16:17], v[102:103], 0, s[0:1]
	v_lshlrev_b32_e32 v82, 11, v18
	v_lshl_add_u64 v[18:19], v[16:17], 0, v[82:83]
	v_add_lshl_u32 v82, v135, s5, 11
	v_lshl_add_u64 v[16:17], v[16:17], 0, v[82:83]
	s_waitcnt vmcnt(3)
	ds_write2_b32 v20, v0, v1 offset1:1
	ds_write2_b32 v20, v2, v3 offset0:2 offset1:3
	s_waitcnt vmcnt(2)
	ds_write2_b32 v21, v4, v5 offset1:1
	ds_write2_b32 v21, v6, v7 offset0:2 offset1:3
	s_waitcnt vmcnt(1)
	ds_write2_b32 v29, v8, v9 offset1:1
	ds_write2_b32 v30, v10, v11 offset1:1
	s_waitcnt vmcnt(0)
	ds_write2_b32 v22, v12, v13 offset1:1
	ds_write2_b32 v22, v14, v15 offset0:2 offset1:3
	s_waitcnt lgkmcnt(0)
	s_barrier
	ds_read2_b32 v[0:1], v131 offset1:129
	ds_read2_b32 v[2:3], v23 offset0:2 offset1:131
	ds_read2_b32 v[4:5], v24 offset0:4 offset1:133
	ds_read2_b32 v[6:7], v25 offset0:6 offset1:135
	ds_read2_b32 v[8:9], v152 offset1:129
	ds_read2_b32 v[10:11], v26 offset0:2 offset1:131
	ds_read2_b32 v[12:13], v27 offset0:4 offset1:133
	ds_read2_b32 v[14:15], v28 offset0:6 offset1:135
	s_waitcnt lgkmcnt(7)
	v_cvt_pk_bf16_f32 v0, v0, v1
	s_waitcnt lgkmcnt(6)
	v_cvt_pk_bf16_f32 v1, v2, v3
	s_waitcnt lgkmcnt(5)
	v_cvt_pk_bf16_f32 v2, v4, v5
	s_waitcnt lgkmcnt(4)
	v_cvt_pk_bf16_f32 v3, v6, v7
	s_waitcnt lgkmcnt(3)
	v_cvt_pk_bf16_f32 v4, v8, v9
	s_waitcnt lgkmcnt(2)
	v_cvt_pk_bf16_f32 v5, v10, v11
	s_waitcnt lgkmcnt(1)
	v_cvt_pk_bf16_f32 v6, v12, v13
	s_waitcnt lgkmcnt(0)
	v_cvt_pk_bf16_f32 v7, v14, v15
	global_store_dwordx4 v[18:19], v[0:3], off
	global_store_dwordx4 v[16:17], v[4:7], off
	s_barrier
	s_branch .LBB0_21
